# phase 11 LN1: also the adaLN scale/shift slices (fixed within an iteration) are loaded once right after their address is formed; re-loads become v_mov behind the wait that covered them
# baseline (speedup 1.0000x reference)
.Lp11_ln:
	v_and_b32_e32 v2, 60, v206
	v_lshl_add_u32 v18, s2, 5, v2
	s_movk_i32 s14, 0x4000
	v_cmp_gt_i32_e32 vcc, s14, v18
	s_and_saveexec_b64 s[14:15], vcc
	s_cbranch_execz .LBB0_1365
	v_mbcnt_lo_u32_b32 v3, -1, 0
	v_mbcnt_hi_u32_b32 v3, -1, v3
	v_and_b32_e32 v7, 64, v3
	v_add_u32_e32 v7, 64, v7
	v_xor_b32_e32 v8, 32, v3
	v_cmp_lt_i32_e32 vcc, v8, v7
	v_lshlrev_b32_e32 v2, 3, v1
	v_and_b32_e32 v2, 0x1f8, v2
	v_cndmask_b32_e32 v8, v3, v8, vcc
	v_lshlrev_b32_e32 v71, 2, v8
	v_xor_b32_e32 v8, 16, v3
	v_cmp_lt_i32_e32 vcc, v8, v7
	v_mov_b32_e32 v21, 0
	v_lshlrev_b32_e32 v20, 1, v2
	v_cndmask_b32_e32 v8, v3, v8, vcc
	v_lshlrev_b32_e32 v72, 2, v8
	v_xor_b32_e32 v8, 8, v3
	v_cmp_lt_i32_e32 vcc, v8, v7
	v_lshl_add_u64 v[4:5], s[66:67], 0, v[20:21]
	s_lshl_b32 s19, s70, 5
	v_cndmask_b32_e32 v8, v3, v8, vcc
	v_lshlrev_b32_e32 v73, 2, v8
	v_xor_b32_e32 v8, 4, v3
	v_cmp_lt_i32_e32 vcc, v8, v7
	v_lshlrev_b32_e32 v20, 2, v2
	s_waitcnt lgkmcnt(0)
	v_lshl_add_u64 v[24:25], s[4:5], 0, v[20:21]
	v_cndmask_b32_e32 v8, v3, v8, vcc
	v_lshlrev_b32_e32 v74, 2, v8
	v_xor_b32_e32 v8, 2, v3
	v_cmp_lt_i32_e32 vcc, v8, v7
	v_lshl_add_u64 v[26:27], s[6:7], 0, v[20:21]
	s_add_u32 s6, s66, 0x1a00000
	v_cndmask_b32_e32 v8, v3, v8, vcc
	v_lshlrev_b32_e32 v75, 2, v8
	v_xor_b32_e32 v8, 1, v3
	v_cmp_lt_i32_e32 vcc, v8, v7
	s_mov_b64 s[4:5], 0x9c00000
	s_mov_b64 s[16:17], 0x5c00000
	v_or_b32_e32 v6, 0x200, v2
	s_addc_u32 s7, s67, 0
	v_cndmask_b32_e32 v3, v3, v8, vcc
	v_lshl_add_u64 v[28:29], v[4:5], 0, s[4:5]
	s_mov_b64 s[4:5], 0x1c00000
	s_mov_b32 s22, 0x3727c5ac
	v_lshl_add_u64 v[22:23], v[4:5], 0, s[16:17]
	v_lshlrev_b32_e32 v76, 2, v3
	v_lshl_add_u64 v[30:31], v[4:5], 0, s[4:5]
	s_mov_b64 s[4:5], 0
	s_movk_i32 s20, 0x1fff
	s_movk_i32 s21, 0x6000
	v_mov_b64_e32 v[32:33], s[6:7]
	s_mov_b64 s[6:7], 0x4000
	s_mov_b64 s[16:17], 0x3000
	v_lshlrev_b32_e32 v20, 2, v2
	s_mov_b32 s18, 0x3a800000
	v_lshlrev_b32_e32 v34, 2, v6
	v_mov_b32_e32 v35, v21
	v_mov_b64_e32 v[36:37], s[22:23]
	s_mov_b32 s22, 0x800000
	s_movk_i32 s23, 0x3fff
	global_load_dwordx4 v[130:133], v[24:25], off offset:16
	global_load_dwordx4 v[134:137], v[24:25], off
	global_load_dwordx4 v[138:141], v[26:27], off offset:16
	global_load_dwordx4 v[142:145], v[26:27], off
	global_load_dwordx4 v[162:165], v[24:25], off offset:2064
	global_load_dwordx4 v[166:169], v[24:25], off offset:2048
	global_load_dwordx4 v[170:173], v[26:27], off offset:2048
	global_load_dwordx4 v[174:177], v[26:27], off offset:2064
	s_waitcnt vmcnt(0)
.LBB0_1364:
	v_ashrrev_i32_e32 v19, 31, v18
	v_lshlrev_b64 v[40:41], 11, v[18:19]
	v_lshl_add_u64 v[10:11], v[22:23], 0, v[40:41]
	global_load_dwordx4 v[2:5], v[10:11], off
	global_load_dwordx4 v[6:9], v[10:11], off offset:1024
	v_add_u32_e32 v10, 1, v18
	v_ashrrev_i32_e32 v11, 31, v10
	v_lshlrev_b64 v[56:57], 11, v[10:11]
	v_lshl_add_u64 v[38:39], v[22:23], 0, v[56:57]
	global_load_dwordx4 v[10:13], v[38:39], off
	global_load_dwordx4 v[14:17], v[38:39], off offset:1024
	v_cmp_lt_i32_e32 vcc, s20, v18
	v_lshl_add_u64 v[110:111], v[28:29], 0, v[40:41]
	v_lshl_add_u64 v[114:115], v[30:31], 0, v[40:41]
	s_waitcnt vmcnt(0)
	v_lshlrev_b32_e32 v38, 16, v5
	v_and_b32_e32 v39, 0xffff0000, v5
	v_lshlrev_b32_e32 v42, 16, v4
	v_and_b32_e32 v43, 0xffff0000, v4
	v_lshlrev_b32_e32 v4, 16, v3
	v_lshlrev_b32_e32 v58, 16, v10
	v_and_b32_e32 v5, 0xffff0000, v3
	v_lshlrev_b32_e32 v48, 16, v2
	v_and_b32_e32 v49, 0xffff0000, v2
	v_lshlrev_b32_e32 v2, 16, v9
	v_and_b32_e32 v3, 0xffff0000, v9
	v_lshlrev_b32_e32 v50, 16, v8
	v_and_b32_e32 v51, 0xffff0000, v8
	v_lshlrev_b32_e32 v8, 16, v7
	v_and_b32_e32 v9, 0xffff0000, v7
	v_lshlrev_b32_e32 v52, 16, v6
	v_and_b32_e32 v53, 0xffff0000, v6
	v_lshlrev_b32_e32 v6, 16, v13
	v_and_b32_e32 v7, 0xffff0000, v13
	v_lshlrev_b32_e32 v54, 16, v12
	v_and_b32_e32 v55, 0xffff0000, v12
	v_lshlrev_b32_e32 v12, 16, v11
	v_and_b32_e32 v13, 0xffff0000, v11
	v_and_b32_e32 v59, 0xffff0000, v10
	v_lshlrev_b32_e32 v10, 16, v17
	v_and_b32_e32 v11, 0xffff0000, v17
	v_lshlrev_b32_e32 v62, 16, v16
	v_and_b32_e32 v63, 0xffff0000, v16
	v_lshlrev_b32_e32 v16, 16, v15
	v_and_b32_e32 v17, 0xffff0000, v15
	v_add_f32_e32 v15, 0, v58
	v_add_f32_e32 v19, 0, v48
	v_add_f32_e32 v15, v15, v59
	v_lshlrev_b32_e32 v90, 16, v14
	v_and_b32_e32 v91, 0xffff0000, v14
	v_add_f32_e32 v14, v19, v49
	v_add_f32_e32 v15, v15, v12
	v_add_f32_e32 v14, v14, v4
	v_add_f32_e32 v15, v15, v13
	v_add_f32_e32 v14, v14, v5
	v_add_f32_e32 v15, v15, v54
	v_add_f32_e32 v14, v14, v42
	v_add_f32_e32 v15, v15, v55
	v_add_f32_e32 v14, v14, v43
	v_add_f32_e32 v15, v15, v6
	v_add_f32_e32 v14, v14, v38
	v_add_f32_e32 v15, v15, v7
	v_add_f32_e32 v14, v14, v39
	v_add_f32_e32 v15, v15, v90
	v_add_f32_e32 v14, v14, v52
	v_add_f32_e32 v15, v15, v91
	v_add_f32_e32 v14, v14, v53
	v_add_f32_e32 v15, v15, v16
	v_add_f32_e32 v14, v14, v8
	v_add_f32_e32 v15, v15, v17
	v_add_f32_e32 v14, v14, v9
	v_add_f32_e32 v15, v15, v62
	v_add_f32_e32 v14, v14, v50
	v_add_f32_e32 v15, v15, v63
	v_add_f32_e32 v14, v14, v51
	v_add_f32_e32 v15, v15, v10
	v_add_f32_e32 v14, v14, v2
	v_add_f32_e32 v15, v15, v11
	v_add_f32_e32 v14, v14, v3
	ds_bpermute_b32 v44, v71, v15
	ds_bpermute_b32 v19, v71, v14
	s_waitcnt lgkmcnt(1)
	v_add_f32_e32 v15, v15, v44
	s_waitcnt lgkmcnt(0)
	v_add_f32_e32 v14, v14, v19
	ds_bpermute_b32 v44, v72, v15
	ds_bpermute_b32 v19, v72, v14
	s_waitcnt lgkmcnt(1)
	v_add_f32_e32 v15, v15, v44
	s_waitcnt lgkmcnt(0)
	v_add_f32_e32 v14, v14, v19
	ds_bpermute_b32 v44, v73, v15
	ds_bpermute_b32 v19, v73, v14
	s_waitcnt lgkmcnt(1)
	v_add_f32_e32 v15, v15, v44
	s_waitcnt lgkmcnt(0)
	v_add_f32_e32 v14, v14, v19
	ds_bpermute_b32 v44, v74, v15
	ds_bpermute_b32 v19, v74, v14
	s_waitcnt lgkmcnt(1)
	v_add_f32_e32 v15, v15, v44
	s_waitcnt lgkmcnt(0)
	v_add_f32_e32 v14, v14, v19
	ds_bpermute_b32 v19, v75, v14
	ds_bpermute_b32 v60, v75, v15
	s_waitcnt lgkmcnt(1)
	v_add_f32_e32 v14, v14, v19
	ds_bpermute_b32 v19, v76, v14
	s_waitcnt lgkmcnt(1)
	v_add_f32_e32 v15, v15, v60
	ds_bpermute_b32 v60, v76, v15
	s_waitcnt lgkmcnt(1)
	v_add_f32_e32 v14, v14, v19
	v_mul_f32_e32 v14, 0x3a800000, v14
	s_waitcnt lgkmcnt(0)
	v_add_f32_e32 v15, v15, v60
	v_pk_add_f32 v[106:107], v[2:3], v[14:15] op_sel_hi:[1,0] neg_lo:[0,1] neg_hi:[0,1]
	v_mul_f32_e32 v2, 0x3a800000, v15
	v_pk_add_f32 v[92:93], v[48:49], v[14:15] op_sel_hi:[1,0] neg_lo:[0,1] neg_hi:[0,1]
	v_pk_add_f32 v[60:61], v[58:59], v[2:3] op_sel_hi:[1,0] neg_lo:[0,1] neg_hi:[0,1]
	v_pk_add_f32 v[98:99], v[38:39], v[14:15] op_sel_hi:[1,0] neg_lo:[0,1] neg_hi:[0,1]
	v_mov_b32_e32 v39, v93
	v_mov_b32_e32 v38, v61
	v_pk_add_f32 v[94:95], v[4:5], v[14:15] op_sel_hi:[1,0] neg_lo:[0,1] neg_hi:[0,1]
	v_pk_add_f32 v[96:97], v[42:43], v[14:15] op_sel_hi:[1,0] neg_lo:[0,1] neg_hi:[0,1]
	v_pk_add_f32 v[100:101], v[52:53], v[14:15] op_sel_hi:[1,0] neg_lo:[0,1] neg_hi:[0,1]
	v_pk_add_f32 v[102:103], v[8:9], v[14:15] op_sel_hi:[1,0] neg_lo:[0,1] neg_hi:[0,1]
	v_pk_add_f32 v[104:105], v[50:51], v[14:15] op_sel_hi:[1,0] neg_lo:[0,1] neg_hi:[0,1]
	v_mov_b32_e32 v15, v92
	v_pk_add_f32 v[64:65], v[12:13], v[2:3] op_sel_hi:[1,0] neg_lo:[0,1] neg_hi:[0,1]
	v_mov_b32_e32 v14, v60
	v_pk_mul_f32 v[38:39], v[38:39], v[38:39]
	v_mov_b32_e32 v13, v94
	v_mov_b32_e32 v12, v64
	v_pk_fma_f32 v[14:15], v[14:15], v[14:15], v[38:39]
	v_pk_add_f32 v[68:69], v[54:55], v[2:3] op_sel_hi:[1,0] neg_lo:[0,1] neg_hi:[0,1]
	v_pk_add_f32 v[66:67], v[6:7], v[2:3] op_sel_hi:[1,0] neg_lo:[0,1] neg_hi:[0,1]
	v_mov_b32_e32 v7, v95
	v_mov_b32_e32 v6, v65
	v_pk_fma_f32 v[12:13], v[12:13], v[12:13], v[14:15]
	v_pk_add_f32 v[50:51], v[16:17], v[2:3] op_sel_hi:[1,0] neg_lo:[0,1] neg_hi:[0,1]
	v_mov_b32_e32 v17, v96
	v_mov_b32_e32 v16, v68
	v_pk_fma_f32 v[6:7], v[6:7], v[6:7], v[12:13]
	v_mov_b32_e32 v43, v97
	v_mov_b32_e32 v42, v69
	v_pk_fma_f32 v[6:7], v[16:17], v[16:17], v[6:7]
	v_mov_b32_e32 v49, v98
	v_mov_b32_e32 v48, v66
	v_pk_fma_f32 v[6:7], v[42:43], v[42:43], v[6:7]
	v_pk_add_f32 v[52:53], v[90:91], v[2:3] op_sel_hi:[1,0] neg_lo:[0,1] neg_hi:[0,1]
	v_mov_b32_e32 v59, v99
	v_mov_b32_e32 v58, v67
	v_pk_fma_f32 v[6:7], v[48:49], v[48:49], v[6:7]
	v_mov_b32_e32 v90, v52
	v_pk_fma_f32 v[6:7], v[58:59], v[58:59], v[6:7]
	v_mov_b32_e32 v91, v100
	v_pk_fma_f32 v[6:7], v[90:91], v[90:91], v[6:7]
	v_mov_b32_e32 v12, v53
	v_mov_b32_e32 v13, v101
	v_pk_add_f32 v[54:55], v[62:63], v[2:3] op_sel_hi:[1,0] neg_lo:[0,1] neg_hi:[0,1]
	v_pk_fma_f32 v[6:7], v[12:13], v[12:13], v[6:7]
	v_mov_b32_e32 v12, v50
	v_mov_b32_e32 v13, v102
	v_pk_mul_f32 v[4:5], v[104:105], v[104:105]
	v_pk_mul_f32 v[62:63], v[54:55], v[54:55]
	v_pk_fma_f32 v[6:7], v[12:13], v[12:13], v[6:7]
	v_mov_b32_e32 v12, v51
	v_mov_b32_e32 v13, v103
	v_pk_fma_f32 v[6:7], v[12:13], v[12:13], v[6:7]
	v_mov_b32_e32 v12, v62
	v_mov_b32_e32 v13, v4
	v_pk_add_f32 v[58:59], v[10:11], v[2:3] op_sel_hi:[1,0] neg_lo:[0,1] neg_hi:[0,1]
	v_pk_mul_f32 v[8:9], v[106:107], v[106:107]
	v_pk_add_f32 v[6:7], v[12:13], v[6:7]
	v_pk_mul_f32 v[2:3], v[58:59], v[58:59]
	v_mov_b32_e32 v4, v63
	v_pk_add_f32 v[4:5], v[4:5], v[6:7]
	v_mov_b32_e32 v6, v2
	v_mov_b32_e32 v7, v8
	v_pk_add_f32 v[4:5], v[6:7], v[4:5]
	v_mov_b32_e32 v8, v3
	v_pk_add_f32 v[2:3], v[8:9], v[4:5]
	ds_bpermute_b32 v5, v71, v3
	ds_bpermute_b32 v4, v71, v2
	v_add_u32_e32 v6, 2, v18
	v_ashrrev_i32_e32 v7, 31, v6
	v_lshlrev_b64 v[48:49], 11, v[6:7]
	v_lshl_add_u64 v[6:7], v[22:23], 0, v[48:49]
	s_waitcnt lgkmcnt(0)
	v_pk_add_f32 v[2:3], v[2:3], v[4:5]
	ds_bpermute_b32 v5, v72, v3
	ds_bpermute_b32 v4, v72, v2
	global_load_dwordx4 v[14:17], v[6:7], off
	global_load_dwordx4 v[10:13], v[6:7], off offset:1024
	v_add_u32_e32 v6, 3, v18
	v_ashrrev_i32_e32 v7, 31, v6
	v_lshlrev_b64 v[38:39], 11, v[6:7]
	s_waitcnt lgkmcnt(0)
	v_pk_add_f32 v[2:3], v[2:3], v[4:5]
	ds_bpermute_b32 v5, v73, v3
	ds_bpermute_b32 v4, v73, v2
	v_lshl_add_u64 v[42:43], v[22:23], 0, v[38:39]
	v_add_u32_e32 v19, 0xffffe000, v18
	v_lshrrev_b32_e32 v19, 12, v19
	v_add_u32_e32 v19, 1, v19
	s_waitcnt lgkmcnt(0)
	v_pk_add_f32 v[2:3], v[2:3], v[4:5]
	ds_bpermute_b32 v5, v74, v3
	ds_bpermute_b32 v4, v74, v2
	v_cndmask_b32_e32 v19, 0, v19, vcc
	v_add_u32_e32 v18, s19, v18
	s_waitcnt lgkmcnt(0)
	v_pk_add_f32 v[62:63], v[2:3], v[4:5]
	ds_bpermute_b32 v91, v75, v63
	ds_bpermute_b32 v90, v75, v62
	global_load_dwordx4 v[6:9], v[42:43], off
	global_load_dwordx4 v[2:5], v[42:43], off offset:1024
	s_waitcnt lgkmcnt(0)
	v_pk_add_f32 v[42:43], v[62:63], v[90:91]
	ds_bpermute_b32 v63, v76, v43
	ds_bpermute_b32 v62, v76, v42
	v_mad_u64_u32 v[90:91], s[24:25], v19, s21, v[32:33]
	v_lshl_add_u64 v[108:109], v[90:91], 0, s[6:7]
	s_waitcnt lgkmcnt(0)
	v_pk_add_f32 v[42:43], v[42:43], v[62:63]
	s_nop 0
	v_pk_fma_f32 v[62:63], v[42:43], s[18:19], v[36:37] op_sel_hi:[1,0,0]
	v_lshl_add_u64 v[42:43], v[108:109], 0, v[20:21]
	global_load_dwordx4 v[146:149], v[42:43], off
	global_load_dwordx4 v[150:153], v[42:43], off offset:16
	v_mul_f32_e32 v19, 0x4b800000, v63
	v_cmp_gt_f32_e32 vcc, s22, v63
	s_nop 1
	v_cndmask_b32_e32 v19, v63, v19, vcc
	v_rsq_f32_e32 v19, v19
	s_nop 0
	v_mul_f32_e32 v63, 0x45800000, v19
	v_cndmask_b32_e32 v70, v19, v63, vcc
	v_pk_mul_f32 v[92:93], v[92:93], v[70:71] op_sel_hi:[1,0]
	v_mul_f32_e32 v19, 0x4b800000, v62
	s_waitcnt vmcnt(6)
	v_mov_b32_e32 v44, v130
	v_mov_b32_e32 v45, v131
	v_mov_b32_e32 v46, v132
	v_mov_b32_e32 v47, v133
	v_mov_b32_e32 v78, v134
	v_mov_b32_e32 v79, v135
	v_mov_b32_e32 v80, v136
	v_mov_b32_e32 v81, v137
	v_mov_b32_e32 v82, v138
	v_mov_b32_e32 v83, v139
	v_mov_b32_e32 v84, v140
	v_mov_b32_e32 v85, v141
	v_mov_b32_e32 v86, v142
	v_mov_b32_e32 v87, v143
	v_mov_b32_e32 v88, v144
	v_mov_b32_e32 v89, v145
	v_pk_fma_f32 v[112:113], v[78:79], v[92:93], v[86:87]
	v_pk_mul_f32 v[78:79], v[96:97], v[70:71] op_sel_hi:[1,0]
	v_cmp_gt_f32_e32 vcc, s22, v62
	v_pk_fma_f32 v[96:97], v[44:45], v[78:79], v[82:83]
	v_pk_mul_f32 v[44:45], v[94:95], v[70:71] op_sel_hi:[1,0]
	v_cndmask_b32_e32 v19, v62, v19, vcc
	v_pk_fma_f32 v[94:95], v[80:81], v[44:45], v[88:89]
	v_pk_mul_f32 v[44:45], v[98:99], v[70:71] op_sel_hi:[1,0]
	v_rsq_f32_e32 v19, v19
	v_pk_fma_f32 v[98:99], v[46:47], v[44:45], v[84:85]
	v_cvt_pk_bf16_f32 v44, v112, v113
	v_cvt_pk_bf16_f32 v45, v94, v95
	v_cvt_pk_bf16_f32 v46, v96, v97
	v_cvt_pk_bf16_f32 v47, v98, v99
	global_store_dwordx4 v[110:111], v[44:47], off
	s_nop 1
	v_lshl_add_u64 v[46:47], v[90:91], 0, s[16:17]
	v_lshl_add_u64 v[44:45], v[46:47], 0, v[20:21]
	global_load_dwordx4 v[154:157], v[44:45], off
	global_load_dwordx4 v[158:161], v[44:45], off offset:16
	v_lshl_add_u64 v[46:47], v[46:47], 0, v[34:35]
	global_load_dwordx4 v[186:189], v[46:47], off
	global_load_dwordx4 v[190:193], v[46:47], off offset:16
	v_lshl_add_u64 v[62:63], v[28:29], 0, v[56:57]
	v_lshl_add_u64 v[56:57], v[30:31], 0, v[56:57]
	s_waitcnt vmcnt(5)
	v_mov_b32_e32 v78, v146
	v_mov_b32_e32 v79, v147
	v_mov_b32_e32 v80, v148
	v_mov_b32_e32 v81, v149
	v_pk_add_f32 v[40:41], v[78:79], 1.0 op_sel_hi:[1,0]
	s_waitcnt vmcnt(5)
	v_mov_b32_e32 v82, v150
	v_mov_b32_e32 v83, v151
	v_mov_b32_e32 v84, v152
	v_mov_b32_e32 v85, v153
	v_pk_add_f32 v[78:79], v[82:83], 1.0 op_sel_hi:[1,0]
	v_pk_add_f32 v[80:81], v[80:81], 1.0 op_sel_hi:[1,0]
	v_pk_add_f32 v[82:83], v[84:85], 1.0 op_sel_hi:[1,0]
	s_waitcnt vmcnt(2)
	v_mov_b32_e32 v86, v154
	v_mov_b32_e32 v87, v155
	v_mov_b32_e32 v88, v156
	v_mov_b32_e32 v89, v157
	v_pk_fma_f32 v[40:41], v[40:41], v[112:113], v[86:87]
	s_waitcnt vmcnt(2)
	v_mov_b32_e32 v90, v158
	v_mov_b32_e32 v91, v159
	v_mov_b32_e32 v92, v160
	v_mov_b32_e32 v93, v161
	v_pk_fma_f32 v[84:85], v[78:79], v[96:97], v[90:91]
	v_pk_fma_f32 v[80:81], v[80:81], v[94:95], v[88:89]
	v_pk_fma_f32 v[82:83], v[82:83], v[98:99], v[92:93]
	v_cvt_pk_bf16_f32 v78, v40, v41
	v_cvt_pk_bf16_f32 v79, v80, v81
	v_cvt_pk_bf16_f32 v80, v84, v85
	v_cvt_pk_bf16_f32 v81, v82, v83
	global_store_dwordx4 v[114:115], v[78:81], off
	s_nop 0
	v_pk_mul_f32 v[94:95], v[100:101], v[70:71] op_sel_hi:[1,0]
	v_pk_mul_f32 v[96:97], v[104:105], v[70:71] op_sel_hi:[1,0]
	v_pk_mul_f32 v[98:99], v[102:103], v[70:71] op_sel_hi:[1,0]
	v_pk_mul_f32 v[100:101], v[106:107], v[70:71] op_sel_hi:[1,0]
	v_lshl_add_u64 v[40:41], v[108:109], 0, v[34:35]
	global_load_dwordx4 v[178:181], v[40:41], off
	global_load_dwordx4 v[182:185], v[40:41], off offset:16
	v_mul_f32_e32 v70, 0x45800000, v19
	v_cndmask_b32_e32 v70, v19, v70, vcc
	v_pk_mul_f32 v[60:61], v[60:61], v[70:71] op_sel_hi:[1,0]
	v_pk_mul_f32 v[68:69], v[68:69], v[70:71] op_sel_hi:[1,0]
	v_pk_mul_f32 v[64:65], v[64:65], v[70:71] op_sel_hi:[1,0]
	v_pk_mul_f32 v[66:67], v[66:67], v[70:71] op_sel_hi:[1,0]
	v_lshlrev_b32_e32 v106, 16, v3
	v_and_b32_e32 v107, 0xffff0000, v3
	v_lshlrev_b32_e32 v108, 16, v2
	v_and_b32_e32 v109, 0xffff0000, v2
	v_lshlrev_b32_e32 v102, 16, v8
	v_and_b32_e32 v103, 0xffff0000, v8
	v_lshlrev_b32_e32 v8, 16, v7
	v_lshlrev_b32_e32 v104, 16, v5
	v_and_b32_e32 v105, 0xffff0000, v5
	v_pk_mul_f32 v[50:51], v[50:51], v[70:71] op_sel_hi:[1,0]
	s_waitcnt vmcnt(5)
	v_mov_b32_e32 v78, v162
	v_mov_b32_e32 v79, v163
	v_mov_b32_e32 v80, v164
	v_mov_b32_e32 v81, v165
	v_mov_b32_e32 v82, v166
	v_mov_b32_e32 v83, v167
	v_mov_b32_e32 v84, v168
	v_mov_b32_e32 v85, v169
	v_mov_b32_e32 v86, v170
	v_mov_b32_e32 v87, v171
	v_mov_b32_e32 v88, v172
	v_mov_b32_e32 v89, v173
	v_pk_fma_f32 v[94:95], v[82:83], v[94:95], v[86:87]
	s_waitcnt vmcnt(5)
	v_mov_b32_e32 v90, v174
	v_mov_b32_e32 v91, v175
	v_mov_b32_e32 v92, v176
	v_mov_b32_e32 v93, v177
	v_pk_fma_f32 v[96:97], v[78:79], v[96:97], v[90:91]
	v_pk_fma_f32 v[98:99], v[84:85], v[98:99], v[88:89]
	v_pk_fma_f32 v[100:101], v[80:81], v[100:101], v[92:93]
	v_cvt_pk_bf16_f32 v78, v94, v95
	v_cvt_pk_bf16_f32 v79, v98, v99
	v_cvt_pk_bf16_f32 v80, v96, v97
	v_cvt_pk_bf16_f32 v81, v100, v101
	global_store_dwordx4 v[110:111], v[78:81], off offset:1024
	s_nop 0
	s_waitcnt vmcnt(1)
	v_mov_b32_e32 v78, v178
	v_mov_b32_e32 v79, v179
	v_mov_b32_e32 v80, v180
	v_mov_b32_e32 v81, v181
	v_pk_add_f32 v[78:79], v[78:79], 1.0 op_sel_hi:[1,0]
	s_waitcnt vmcnt(1)
	v_mov_b32_e32 v82, v182
	v_mov_b32_e32 v83, v183
	v_mov_b32_e32 v84, v184
	v_mov_b32_e32 v85, v185
	v_pk_add_f32 v[82:83], v[82:83], 1.0 op_sel_hi:[1,0]
	v_pk_add_f32 v[80:81], v[80:81], 1.0 op_sel_hi:[1,0]
	v_pk_add_f32 v[84:85], v[84:85], 1.0 op_sel_hi:[1,0]
	s_waitcnt vmcnt(1)
	v_mov_b32_e32 v86, v186
	v_mov_b32_e32 v87, v187
	v_mov_b32_e32 v88, v188
	v_mov_b32_e32 v89, v189
	v_pk_fma_f32 v[78:79], v[78:79], v[94:95], v[86:87]
	s_waitcnt vmcnt(1)
	v_mov_b32_e32 v90, v190
	v_mov_b32_e32 v91, v191
	v_mov_b32_e32 v92, v192
	v_mov_b32_e32 v93, v193
	v_pk_fma_f32 v[82:83], v[82:83], v[96:97], v[90:91]
	v_pk_fma_f32 v[80:81], v[80:81], v[98:99], v[88:89]
	v_pk_fma_f32 v[84:85], v[84:85], v[100:101], v[92:93]
	v_cvt_pk_bf16_f32 v78, v78, v79
	v_cvt_pk_bf16_f32 v79, v80, v81
	v_cvt_pk_bf16_f32 v80, v82, v83
	v_cvt_pk_bf16_f32 v81, v84, v85
	global_store_dwordx4 v[114:115], v[78:81], off offset:1024
	s_nop 0
	v_lshlrev_b32_e32 v94, 16, v14
	v_lshlrev_b32_e32 v98, 16, v10
	v_and_b32_e32 v99, 0xffff0000, v10
	v_lshlrev_b32_e32 v10, 16, v6
	v_and_b32_e32 v95, 0xffff0000, v14
	v_lshlrev_b32_e32 v14, 16, v13
	v_lshlrev_b32_e32 v96, 16, v12
	v_and_b32_e32 v97, 0xffff0000, v12
	v_lshlrev_b32_e32 v12, 16, v11
	v_add_f32_e32 v2, 0, v94
	v_add_f32_e32 v3, 0, v10
	v_add_f32_e32 v2, v2, v95
	v_lshlrev_b32_e32 v100, 16, v9
	v_and_b32_e32 v101, 0xffff0000, v9
	v_and_b32_e32 v9, 0xffff0000, v7
	v_and_b32_e32 v7, 0xffff0000, v4
	s_waitcnt vmcnt(2)
	v_mov_b32_e32 v78, v130
	v_mov_b32_e32 v79, v131
	v_mov_b32_e32 v80, v132
	v_mov_b32_e32 v81, v133
	v_mov_b32_e32 v82, v134
	v_mov_b32_e32 v83, v135
	v_mov_b32_e32 v84, v136
	v_mov_b32_e32 v85, v137
	v_mov_b32_e32 v86, v142
	v_mov_b32_e32 v87, v143
	v_mov_b32_e32 v88, v144
	v_mov_b32_e32 v89, v145
	v_pk_fma_f32 v[60:61], v[82:83], v[60:61], v[86:87]
	s_waitcnt vmcnt(2)
	v_mov_b32_e32 v90, v138
	v_mov_b32_e32 v91, v139
	v_mov_b32_e32 v92, v140
	v_mov_b32_e32 v93, v141
	v_pk_fma_f32 v[68:69], v[78:79], v[68:69], v[90:91]
	v_pk_fma_f32 v[90:91], v[84:85], v[64:65], v[88:89]
	v_pk_fma_f32 v[92:93], v[80:81], v[66:67], v[92:93]
	v_cvt_pk_bf16_f32 v64, v60, v61
	v_cvt_pk_bf16_f32 v65, v90, v91
	v_cvt_pk_bf16_f32 v66, v68, v69
	v_cvt_pk_bf16_f32 v67, v92, v93
	global_store_dwordx4 v[62:63], v[64:67], off
	s_nop 0
	s_waitcnt vmcnt(3)
	v_mov_b32_e32 v64, v146
	v_mov_b32_e32 v65, v147
	v_mov_b32_e32 v66, v148
	v_mov_b32_e32 v67, v149
	v_pk_add_f32 v[64:65], v[64:65], 1.0 op_sel_hi:[1,0]
	s_waitcnt vmcnt(3)
	v_mov_b32_e32 v78, v150
	v_mov_b32_e32 v79, v151
	v_mov_b32_e32 v80, v152
	v_mov_b32_e32 v81, v153
	v_pk_add_f32 v[78:79], v[78:79], 1.0 op_sel_hi:[1,0]
	v_pk_add_f32 v[66:67], v[66:67], 1.0 op_sel_hi:[1,0]
	v_pk_add_f32 v[80:81], v[80:81], 1.0 op_sel_hi:[1,0]
	s_waitcnt vmcnt(3)
	v_mov_b32_e32 v82, v154
	v_mov_b32_e32 v83, v155
	v_mov_b32_e32 v84, v156
	v_mov_b32_e32 v85, v157
	v_pk_fma_f32 v[60:61], v[64:65], v[60:61], v[82:83]
	s_waitcnt vmcnt(3)
	v_mov_b32_e32 v86, v158
	v_mov_b32_e32 v87, v159
	v_mov_b32_e32 v88, v160
	v_mov_b32_e32 v89, v161
	v_pk_fma_f32 v[68:69], v[78:79], v[68:69], v[86:87]
	v_pk_fma_f32 v[66:67], v[66:67], v[90:91], v[84:85]
	v_pk_fma_f32 v[78:79], v[80:81], v[92:93], v[88:89]
	v_cvt_pk_bf16_f32 v64, v60, v61
	v_cvt_pk_bf16_f32 v65, v66, v67
	v_cvt_pk_bf16_f32 v66, v68, v69
	v_cvt_pk_bf16_f32 v67, v78, v79
	global_store_dwordx4 v[56:57], v[64:67], off
	s_nop 0
	v_lshlrev_b32_e32 v90, 16, v17
	v_and_b32_e32 v91, 0xffff0000, v17
	v_lshlrev_b32_e32 v92, 16, v16
	v_and_b32_e32 v93, 0xffff0000, v16
	v_lshlrev_b32_e32 v16, 16, v15
	v_and_b32_e32 v17, 0xffff0000, v15
	v_and_b32_e32 v15, 0xffff0000, v13
	v_and_b32_e32 v13, 0xffff0000, v11
	v_and_b32_e32 v11, 0xffff0000, v6
	v_add_f32_e32 v3, v3, v11
	v_add_f32_e32 v2, v2, v16
	v_add_f32_e32 v3, v3, v8
	v_add_f32_e32 v2, v2, v17
	v_add_f32_e32 v3, v3, v9
	v_add_f32_e32 v2, v2, v92
	v_add_f32_e32 v3, v3, v102
	v_add_f32_e32 v2, v2, v93
	v_add_f32_e32 v3, v3, v103
	v_add_f32_e32 v2, v2, v90
	v_add_f32_e32 v3, v3, v100
	v_add_f32_e32 v2, v2, v91
	v_add_f32_e32 v3, v3, v101
	v_add_f32_e32 v2, v2, v98
	v_add_f32_e32 v3, v3, v108
	v_add_f32_e32 v2, v2, v99
	v_add_f32_e32 v3, v3, v109
	v_add_f32_e32 v2, v2, v12
	v_add_f32_e32 v3, v3, v106
	v_lshlrev_b32_e32 v6, 16, v4
	v_add_f32_e32 v2, v2, v13
	v_add_f32_e32 v3, v3, v107
	v_add_f32_e32 v2, v2, v96
	v_add_f32_e32 v3, v3, v6
	v_add_f32_e32 v2, v2, v97
	v_add_f32_e32 v3, v3, v7
	v_add_f32_e32 v2, v2, v14
	v_add_f32_e32 v3, v3, v104
	v_add_f32_e32 v2, v2, v15
	v_add_f32_e32 v3, v3, v105
	ds_bpermute_b32 v4, v71, v2
	ds_bpermute_b32 v5, v71, v3
	s_waitcnt lgkmcnt(1)
	v_add_f32_e32 v19, v2, v4
	s_waitcnt lgkmcnt(0)
	v_add_f32_e32 v77, v3, v5
	v_pk_mul_f32 v[2:3], v[52:53], v[70:71] op_sel_hi:[1,0]
	v_pk_mul_f32 v[4:5], v[54:55], v[70:71] op_sel_hi:[1,0]
	v_pk_mul_f32 v[52:53], v[58:59], v[70:71] op_sel_hi:[1,0]
	ds_bpermute_b32 v110, v72, v19
	s_waitcnt vmcnt(4)
	v_mov_b32_e32 v64, v162
	v_mov_b32_e32 v65, v163
	v_mov_b32_e32 v66, v164
	v_mov_b32_e32 v67, v165
	v_mov_b32_e32 v78, v166
	v_mov_b32_e32 v79, v167
	v_mov_b32_e32 v80, v168
	v_mov_b32_e32 v81, v169
	v_mov_b32_e32 v82, v170
	v_mov_b32_e32 v83, v171
	v_mov_b32_e32 v84, v172
	v_mov_b32_e32 v85, v173
	v_pk_fma_f32 v[54:55], v[78:79], v[2:3], v[82:83]
	s_waitcnt vmcnt(4)
	v_mov_b32_e32 v86, v174
	v_mov_b32_e32 v87, v175
	v_mov_b32_e32 v88, v176
	v_mov_b32_e32 v89, v177
	v_pk_fma_f32 v[78:79], v[64:65], v[4:5], v[86:87]
	v_pk_fma_f32 v[80:81], v[80:81], v[50:51], v[84:85]
	v_pk_fma_f32 v[82:83], v[66:67], v[52:53], v[88:89]
	v_cvt_pk_bf16_f32 v2, v54, v55
	v_cvt_pk_bf16_f32 v3, v80, v81
	v_cvt_pk_bf16_f32 v4, v78, v79
	v_cvt_pk_bf16_f32 v5, v82, v83
	global_store_dwordx4 v[62:63], v[2:5], off offset:1024
	s_nop 0
	ds_bpermute_b32 v2, v72, v77
	s_waitcnt lgkmcnt(1)
	v_add_f32_e32 v3, v19, v110
	ds_bpermute_b32 v4, v73, v3
	s_waitcnt lgkmcnt(1)
	v_add_f32_e32 v2, v77, v2
	ds_bpermute_b32 v5, v73, v2
	s_waitcnt lgkmcnt(1)
	v_add_f32_e32 v3, v3, v4
	ds_bpermute_b32 v4, v74, v3
	s_waitcnt lgkmcnt(1)
	v_add_f32_e32 v2, v2, v5
	ds_bpermute_b32 v5, v74, v2
	s_waitcnt lgkmcnt(1)
	v_add_f32_e32 v3, v3, v4
	ds_bpermute_b32 v4, v75, v3
	s_waitcnt lgkmcnt(1)
	v_add_f32_e32 v2, v2, v5
	ds_bpermute_b32 v5, v75, v2
	s_waitcnt lgkmcnt(1)
	v_add_f32_e32 v3, v3, v4
	ds_bpermute_b32 v4, v76, v3
	s_waitcnt lgkmcnt(1)
	v_add_f32_e32 v2, v2, v5
	ds_bpermute_b32 v5, v76, v2
	s_waitcnt lgkmcnt(1)
	v_add_f32_e32 v3, v3, v4
	s_waitcnt lgkmcnt(0)
	v_add_f32_e32 v4, v2, v5
	v_mul_f32_e32 v2, 0x3a800000, v3
	v_mul_f32_e32 v70, 0x3a800000, v4
	v_pk_add_f32 v[84:85], v[94:95], v[2:3] op_sel_hi:[1,0] neg_lo:[0,1] neg_hi:[0,1]
	v_pk_add_f32 v[10:11], v[10:11], v[70:71] op_sel_hi:[1,0] neg_lo:[0,1] neg_hi:[0,1]
	v_pk_add_f32 v[86:87], v[16:17], v[2:3] op_sel_hi:[1,0] neg_lo:[0,1] neg_hi:[0,1]
	v_pk_add_f32 v[88:89], v[92:93], v[2:3] op_sel_hi:[1,0] neg_lo:[0,1] neg_hi:[0,1]
	v_pk_add_f32 v[90:91], v[90:91], v[2:3] op_sel_hi:[1,0] neg_lo:[0,1] neg_hi:[0,1]
	v_pk_add_f32 v[92:93], v[98:99], v[2:3] op_sel_hi:[1,0] neg_lo:[0,1] neg_hi:[0,1]
	v_pk_add_f32 v[94:95], v[12:13], v[2:3] op_sel_hi:[1,0] neg_lo:[0,1] neg_hi:[0,1]
	v_pk_add_f32 v[96:97], v[96:97], v[2:3] op_sel_hi:[1,0] neg_lo:[0,1] neg_hi:[0,1]
	v_pk_add_f32 v[98:99], v[14:15], v[2:3] op_sel_hi:[1,0] neg_lo:[0,1] neg_hi:[0,1]
	v_pk_add_f32 v[12:13], v[8:9], v[70:71] op_sel_hi:[1,0] neg_lo:[0,1] neg_hi:[0,1]
	v_pk_add_f32 v[2:3], v[106:107], v[70:71] op_sel_hi:[1,0] neg_lo:[0,1] neg_hi:[0,1]
	v_pk_add_f32 v[8:9], v[104:105], v[70:71] op_sel_hi:[1,0] neg_lo:[0,1] neg_hi:[0,1]
	v_mov_b32_e32 v106, v11
	v_mov_b32_e32 v107, v85
	v_pk_add_f32 v[16:17], v[102:103], v[70:71] op_sel_hi:[1,0] neg_lo:[0,1] neg_hi:[0,1]
	v_pk_mul_f32 v[102:103], v[98:99], v[98:99]
	v_mov_b32_e32 v104, v10
	v_mov_b32_e32 v105, v84
	v_pk_add_f32 v[4:5], v[108:109], v[70:71] op_sel_hi:[1,0] neg_lo:[0,1] neg_hi:[0,1]
	v_mov_b32_e32 v108, v12
	v_mov_b32_e32 v109, v86
	v_mov_b32_e32 v112, v13
	v_mov_b32_e32 v113, v87
	v_mov_b32_e32 v114, v16
	v_mov_b32_e32 v115, v88
	v_pk_add_f32 v[14:15], v[100:101], v[70:71] op_sel_hi:[1,0] neg_lo:[0,1] neg_hi:[0,1]
	v_mov_b32_e32 v116, v17
	v_mov_b32_e32 v117, v89
	v_mov_b32_e32 v118, v14
	v_mov_b32_e32 v119, v90
	v_mov_b32_e32 v120, v15
	v_mov_b32_e32 v121, v91
	v_mov_b32_e32 v122, v4
	v_mov_b32_e32 v123, v92
	v_mov_b32_e32 v124, v5
	v_mov_b32_e32 v125, v93
	v_pk_add_f32 v[6:7], v[6:7], v[70:71] op_sel_hi:[1,0] neg_lo:[0,1] neg_hi:[0,1]
	v_mov_b32_e32 v126, v2
	v_mov_b32_e32 v127, v94
	v_pk_mul_f32 v[100:101], v[96:97], v[96:97]
	v_pk_mul_f32 v[110:111], v[6:7], v[6:7]
	v_mov_b32_e32 v128, v3
	v_mov_b32_e32 v129, v95
	s_waitcnt vmcnt(5)
	v_mov_b32_e32 v50, v182
	v_mov_b32_e32 v51, v183
	v_mov_b32_e32 v52, v184
	v_mov_b32_e32 v53, v185
	v_pk_add_f32 v[50:51], v[50:51], 1.0 op_sel_hi:[1,0]
	s_waitcnt vmcnt(5)
	v_mov_b32_e32 v58, v178
	v_mov_b32_e32 v59, v179
	v_mov_b32_e32 v60, v180
	v_mov_b32_e32 v61, v181
	v_pk_add_f32 v[58:59], v[58:59], 1.0 op_sel_hi:[1,0]
	v_pk_add_f32 v[60:61], v[60:61], 1.0 op_sel_hi:[1,0]
	v_pk_add_f32 v[52:53], v[52:53], 1.0 op_sel_hi:[1,0]
	s_waitcnt vmcnt(5)
	v_mov_b32_e32 v62, v190
	v_mov_b32_e32 v63, v191
	v_mov_b32_e32 v64, v192
	v_mov_b32_e32 v65, v193
	v_mov_b32_e32 v66, v186
	v_mov_b32_e32 v67, v187
	v_mov_b32_e32 v68, v188
	v_mov_b32_e32 v69, v189
	v_pk_fma_f32 v[54:55], v[58:59], v[54:55], v[66:67]
	v_pk_fma_f32 v[58:59], v[50:51], v[78:79], v[62:63]
	v_pk_fma_f32 v[60:61], v[60:61], v[80:81], v[68:69]
	v_pk_fma_f32 v[62:63], v[52:53], v[82:83], v[64:65]
	v_cvt_pk_bf16_f32 v50, v54, v55
	v_cvt_pk_bf16_f32 v51, v60, v61
	v_cvt_pk_bf16_f32 v52, v58, v59
	v_cvt_pk_bf16_f32 v53, v62, v63
	global_store_dwordx4 v[56:57], v[50:53], off offset:1024
	s_nop 0
	v_pk_mul_f32 v[66:67], v[8:9], v[8:9]
	v_pk_mul_f32 v[68:69], v[106:107], v[106:107]
	v_mov_b32_e32 v80, v66
	v_mov_b32_e32 v81, v102
	v_mov_b32_e32 v102, v67
	v_pk_fma_f32 v[66:67], v[104:105], v[104:105], v[68:69]
	v_mov_b32_e32 v78, v110
	v_pk_fma_f32 v[66:67], v[108:109], v[108:109], v[66:67]
	v_mov_b32_e32 v79, v100
	v_pk_fma_f32 v[66:67], v[112:113], v[112:113], v[66:67]
	v_mov_b32_e32 v100, v111
	v_pk_fma_f32 v[66:67], v[114:115], v[114:115], v[66:67]
	s_nop 0
	v_pk_fma_f32 v[66:67], v[116:117], v[116:117], v[66:67]
	s_nop 0
	v_pk_fma_f32 v[66:67], v[118:119], v[118:119], v[66:67]
	s_nop 0
	v_pk_fma_f32 v[66:67], v[120:121], v[120:121], v[66:67]
	s_nop 0
	v_pk_fma_f32 v[66:67], v[122:123], v[122:123], v[66:67]
	s_nop 0
	v_pk_fma_f32 v[66:67], v[124:125], v[124:125], v[66:67]
	s_nop 0
	v_pk_fma_f32 v[66:67], v[126:127], v[126:127], v[66:67]
	s_nop 0
	v_pk_fma_f32 v[66:67], v[128:129], v[128:129], v[66:67]
	s_nop 0
	v_pk_add_f32 v[66:67], v[78:79], v[66:67]
	s_nop 0
	v_pk_add_f32 v[66:67], v[100:101], v[66:67]
	s_nop 0
	v_pk_add_f32 v[66:67], v[80:81], v[66:67]
	s_nop 0
	v_pk_add_f32 v[66:67], v[102:103], v[66:67]
	ds_bpermute_b32 v69, v71, v67
	ds_bpermute_b32 v68, v71, v66
	s_waitcnt lgkmcnt(0)
	v_pk_add_f32 v[66:67], v[66:67], v[68:69]
	ds_bpermute_b32 v69, v72, v67
	ds_bpermute_b32 v68, v72, v66
	s_waitcnt lgkmcnt(0)
	v_pk_add_f32 v[66:67], v[66:67], v[68:69]
	ds_bpermute_b32 v69, v73, v67
	ds_bpermute_b32 v68, v73, v66
	s_waitcnt lgkmcnt(0)
	v_pk_add_f32 v[66:67], v[66:67], v[68:69]
	ds_bpermute_b32 v69, v74, v67
	ds_bpermute_b32 v68, v74, v66
	s_waitcnt lgkmcnt(0)
	v_pk_add_f32 v[66:67], v[66:67], v[68:69]
	ds_bpermute_b32 v69, v75, v67
	ds_bpermute_b32 v68, v75, v66
	s_waitcnt lgkmcnt(0)
	v_pk_add_f32 v[66:67], v[66:67], v[68:69]
	ds_bpermute_b32 v69, v76, v67
	ds_bpermute_b32 v68, v76, v66
	s_waitcnt lgkmcnt(0)
	v_pk_add_f32 v[66:67], v[66:67], v[68:69]
	s_nop 0
	v_pk_fma_f32 v[66:67], v[66:67], s[18:19], v[36:37] op_sel_hi:[1,0,0]
	v_lshl_add_u64 v[68:69], v[28:29], 0, v[48:49]
	v_mul_f32_e32 v19, 0x4b800000, v67
	v_cmp_gt_f32_e32 vcc, s22, v67
	s_nop 1
	v_cndmask_b32_e32 v19, v67, v19, vcc
	v_rsq_f32_e32 v19, v19
	s_nop 0
	v_mul_f32_e32 v67, 0x45800000, v19
	v_cndmask_b32_e32 v70, v19, v67, vcc
	v_pk_mul_f32 v[78:79], v[84:85], v[70:71] op_sel_hi:[1,0]
	v_pk_mul_f32 v[80:81], v[88:89], v[70:71] op_sel_hi:[1,0]
	v_pk_mul_f32 v[82:83], v[86:87], v[70:71] op_sel_hi:[1,0]
	v_pk_mul_f32 v[84:85], v[90:91], v[70:71] op_sel_hi:[1,0]
	s_waitcnt vmcnt(6)
	v_mov_b32_e32 v50, v130
	v_mov_b32_e32 v51, v131
	v_mov_b32_e32 v52, v132
	v_mov_b32_e32 v53, v133
	v_mov_b32_e32 v54, v134
	v_mov_b32_e32 v55, v135
	v_mov_b32_e32 v56, v136
	v_mov_b32_e32 v57, v137
	v_mov_b32_e32 v58, v138
	v_mov_b32_e32 v59, v139
	v_mov_b32_e32 v60, v140
	v_mov_b32_e32 v61, v141
	v_mov_b32_e32 v62, v142
	v_mov_b32_e32 v63, v143
	v_mov_b32_e32 v64, v144
	v_mov_b32_e32 v65, v145
	v_pk_fma_f32 v[78:79], v[54:55], v[78:79], v[62:63]
	v_pk_fma_f32 v[80:81], v[50:51], v[80:81], v[58:59]
	v_pk_fma_f32 v[82:83], v[56:57], v[82:83], v[64:65]
	v_pk_fma_f32 v[84:85], v[52:53], v[84:85], v[60:61]
	v_cvt_pk_bf16_f32 v50, v78, v79
	v_cvt_pk_bf16_f32 v51, v82, v83
	v_cvt_pk_bf16_f32 v52, v80, v81
	v_cvt_pk_bf16_f32 v53, v84, v85
	global_store_dwordx4 v[68:69], v[50:53], off
	s_nop 0
	v_lshl_add_u64 v[86:87], v[30:31], 0, v[48:49]
	v_mul_f32_e32 v19, 0x4b800000, v66
	v_cmp_gt_f32_e32 vcc, s22, v66
	s_waitcnt vmcnt(7)
	v_mov_b32_e32 v50, v146
	v_mov_b32_e32 v51, v147
	v_mov_b32_e32 v52, v148
	v_mov_b32_e32 v53, v149
	v_pk_add_f32 v[48:49], v[50:51], 1.0 op_sel_hi:[1,0]
	s_waitcnt vmcnt(7)
	v_mov_b32_e32 v54, v150
	v_mov_b32_e32 v55, v151
	v_mov_b32_e32 v56, v152
	v_mov_b32_e32 v57, v153
	v_pk_add_f32 v[50:51], v[54:55], 1.0 op_sel_hi:[1,0]
	v_pk_add_f32 v[52:53], v[52:53], 1.0 op_sel_hi:[1,0]
	v_pk_add_f32 v[54:55], v[56:57], 1.0 op_sel_hi:[1,0]
	s_waitcnt vmcnt(7)
	v_mov_b32_e32 v58, v154
	v_mov_b32_e32 v59, v155
	v_mov_b32_e32 v60, v156
	v_mov_b32_e32 v61, v157
	v_pk_fma_f32 v[48:49], v[48:49], v[78:79], v[58:59]
	s_waitcnt vmcnt(7)
	v_mov_b32_e32 v62, v158
	v_mov_b32_e32 v63, v159
	v_mov_b32_e32 v64, v160
	v_mov_b32_e32 v65, v161
	v_pk_fma_f32 v[50:51], v[50:51], v[80:81], v[62:63]
	v_pk_fma_f32 v[52:53], v[52:53], v[82:83], v[60:61]
	v_pk_fma_f32 v[54:55], v[54:55], v[84:85], v[64:65]
	v_cvt_pk_bf16_f32 v48, v48, v49
	v_cvt_pk_bf16_f32 v49, v52, v53
	v_cvt_pk_bf16_f32 v50, v50, v51
	v_cvt_pk_bf16_f32 v51, v54, v55
	global_store_dwordx4 v[86:87], v[48:51], off
	s_nop 0
	v_pk_mul_f32 v[64:65], v[92:93], v[70:71] op_sel_hi:[1,0]
	v_pk_mul_f32 v[78:79], v[96:97], v[70:71] op_sel_hi:[1,0]
	v_pk_mul_f32 v[80:81], v[94:95], v[70:71] op_sel_hi:[1,0]
	v_pk_mul_f32 v[82:83], v[98:99], v[70:71] op_sel_hi:[1,0]
	v_cndmask_b32_e32 v19, v66, v19, vcc
	v_rsq_f32_e32 v19, v19
	s_waitcnt vmcnt(8)
	v_mov_b32_e32 v48, v162
	v_mov_b32_e32 v49, v163
	v_mov_b32_e32 v50, v164
	v_mov_b32_e32 v51, v165
	v_mov_b32_e32 v52, v166
	v_mov_b32_e32 v53, v167
	v_mov_b32_e32 v54, v168
	v_mov_b32_e32 v55, v169
	v_mov_b32_e32 v56, v170
	v_mov_b32_e32 v57, v171
	v_mov_b32_e32 v58, v172
	v_mov_b32_e32 v59, v173
	v_pk_fma_f32 v[64:65], v[52:53], v[64:65], v[56:57]
	s_waitcnt vmcnt(8)
	v_mov_b32_e32 v60, v174
	v_mov_b32_e32 v61, v175
	v_mov_b32_e32 v62, v176
	v_mov_b32_e32 v63, v177
	v_pk_fma_f32 v[78:79], v[48:49], v[78:79], v[60:61]
	v_pk_fma_f32 v[80:81], v[54:55], v[80:81], v[58:59]
	v_pk_fma_f32 v[82:83], v[50:51], v[82:83], v[62:63]
	v_cvt_pk_bf16_f32 v48, v64, v65
	v_cvt_pk_bf16_f32 v49, v80, v81
	v_cvt_pk_bf16_f32 v50, v78, v79
	v_cvt_pk_bf16_f32 v51, v82, v83
	global_store_dwordx4 v[68:69], v[48:51], off offset:1024
	s_nop 0
	v_mul_f32_e32 v66, 0x45800000, v19
	v_cndmask_b32_e32 v66, v19, v66, vcc
	v_pk_mul_f32 v[10:11], v[10:11], v[66:67] op_sel_hi:[1,0]
	v_pk_mul_f32 v[16:17], v[16:17], v[66:67] op_sel_hi:[1,0]
	v_pk_mul_f32 v[12:13], v[12:13], v[66:67] op_sel_hi:[1,0]
	v_pk_mul_f32 v[14:15], v[14:15], v[66:67] op_sel_hi:[1,0]
	v_pk_mul_f32 v[4:5], v[4:5], v[66:67] op_sel_hi:[1,0]
	v_pk_mul_f32 v[6:7], v[6:7], v[66:67] op_sel_hi:[1,0]
	v_pk_mul_f32 v[2:3], v[2:3], v[66:67] op_sel_hi:[1,0]
	v_pk_mul_f32 v[8:9], v[8:9], v[66:67] op_sel_hi:[1,0]
	v_cmp_lt_i32_e32 vcc, s23, v18
	s_or_b64 s[4:5], vcc, s[4:5]
	s_waitcnt vmcnt(9)
	v_mov_b32_e32 v48, v178
	v_mov_b32_e32 v49, v179
	v_mov_b32_e32 v50, v180
	v_mov_b32_e32 v51, v181
	v_pk_add_f32 v[48:49], v[48:49], 1.0 op_sel_hi:[1,0]
	s_waitcnt vmcnt(9)
	v_mov_b32_e32 v52, v182
	v_mov_b32_e32 v53, v183
	v_mov_b32_e32 v54, v184
	v_mov_b32_e32 v55, v185
	v_pk_add_f32 v[52:53], v[52:53], 1.0 op_sel_hi:[1,0]
	v_pk_add_f32 v[50:51], v[50:51], 1.0 op_sel_hi:[1,0]
	v_pk_add_f32 v[54:55], v[54:55], 1.0 op_sel_hi:[1,0]
	s_waitcnt vmcnt(9)
	v_mov_b32_e32 v56, v186
	v_mov_b32_e32 v57, v187
	v_mov_b32_e32 v58, v188
	v_mov_b32_e32 v59, v189
	v_pk_fma_f32 v[48:49], v[48:49], v[64:65], v[56:57]
	s_waitcnt vmcnt(9)
	v_mov_b32_e32 v60, v190
	v_mov_b32_e32 v61, v191
	v_mov_b32_e32 v62, v192
	v_mov_b32_e32 v63, v193
	v_pk_fma_f32 v[52:53], v[52:53], v[78:79], v[60:61]
	v_pk_fma_f32 v[50:51], v[50:51], v[80:81], v[58:59]
	v_pk_fma_f32 v[54:55], v[54:55], v[82:83], v[62:63]
	v_cvt_pk_bf16_f32 v48, v48, v49
	v_cvt_pk_bf16_f32 v49, v50, v51
	v_cvt_pk_bf16_f32 v50, v52, v53
	v_cvt_pk_bf16_f32 v51, v54, v55
	global_store_dwordx4 v[86:87], v[48:51], off offset:1024
	s_nop 0
	v_lshl_add_u64 v[64:65], v[28:29], 0, v[38:39]
	v_lshl_add_u64 v[38:39], v[30:31], 0, v[38:39]
	s_waitcnt vmcnt(10)
	v_mov_b32_e32 v48, v130
	v_mov_b32_e32 v49, v131
	v_mov_b32_e32 v50, v132
	v_mov_b32_e32 v51, v133
	v_mov_b32_e32 v52, v134
	v_mov_b32_e32 v53, v135
	v_mov_b32_e32 v54, v136
	v_mov_b32_e32 v55, v137
	v_mov_b32_e32 v56, v142
	v_mov_b32_e32 v57, v143
	v_mov_b32_e32 v58, v144
	v_mov_b32_e32 v59, v145
	v_pk_fma_f32 v[56:57], v[52:53], v[10:11], v[56:57]
	s_waitcnt vmcnt(10)
	v_mov_b32_e32 v60, v138
	v_mov_b32_e32 v61, v139
	v_mov_b32_e32 v62, v140
	v_mov_b32_e32 v63, v141
	v_pk_fma_f32 v[60:61], v[48:49], v[16:17], v[60:61]
	v_pk_fma_f32 v[58:59], v[54:55], v[12:13], v[58:59]
	v_pk_fma_f32 v[62:63], v[50:51], v[14:15], v[62:63]
	v_cvt_pk_bf16_f32 v10, v56, v57
	v_cvt_pk_bf16_f32 v11, v58, v59
	v_cvt_pk_bf16_f32 v12, v60, v61
	v_cvt_pk_bf16_f32 v13, v62, v63
	global_store_dwordx4 v[64:65], v[10:13], off
	s_nop 0
	s_waitcnt vmcnt(11)
	v_mov_b32_e32 v10, v146
	v_mov_b32_e32 v11, v147
	v_mov_b32_e32 v12, v148
	v_mov_b32_e32 v13, v149
	v_pk_add_f32 v[10:11], v[10:11], 1.0 op_sel_hi:[1,0]
	s_waitcnt vmcnt(11)
	v_mov_b32_e32 v14, v150
	v_mov_b32_e32 v15, v151
	v_mov_b32_e32 v16, v152
	v_mov_b32_e32 v17, v153
	v_pk_add_f32 v[14:15], v[14:15], 1.0 op_sel_hi:[1,0]
	v_pk_add_f32 v[12:13], v[12:13], 1.0 op_sel_hi:[1,0]
	v_pk_add_f32 v[16:17], v[16:17], 1.0 op_sel_hi:[1,0]
	s_waitcnt vmcnt(11)
	v_mov_b32_e32 v48, v154
	v_mov_b32_e32 v49, v155
	v_mov_b32_e32 v50, v156
	v_mov_b32_e32 v51, v157
	v_pk_fma_f32 v[10:11], v[10:11], v[56:57], v[48:49]
	s_waitcnt vmcnt(11)
	v_mov_b32_e32 v52, v158
	v_mov_b32_e32 v53, v159
	v_mov_b32_e32 v54, v160
	v_mov_b32_e32 v55, v161
	v_pk_fma_f32 v[14:15], v[14:15], v[60:61], v[52:53]
	v_pk_fma_f32 v[12:13], v[12:13], v[58:59], v[50:51]
	v_pk_fma_f32 v[16:17], v[16:17], v[62:63], v[54:55]
	v_cvt_pk_bf16_f32 v10, v10, v11
	v_cvt_pk_bf16_f32 v11, v12, v13
	v_cvt_pk_bf16_f32 v12, v14, v15
	v_cvt_pk_bf16_f32 v13, v16, v17
	global_store_dwordx4 v[38:39], v[10:13], off
	s_nop 0
	s_waitcnt vmcnt(12)
	v_mov_b32_e32 v10, v162
	v_mov_b32_e32 v11, v163
	v_mov_b32_e32 v12, v164
	v_mov_b32_e32 v13, v165
	v_mov_b32_e32 v14, v166
	v_mov_b32_e32 v15, v167
	v_mov_b32_e32 v16, v168
	v_mov_b32_e32 v17, v169
	v_mov_b32_e32 v42, v170
	v_mov_b32_e32 v43, v171
	v_mov_b32_e32 v44, v172
	v_mov_b32_e32 v45, v173
	v_pk_fma_f32 v[42:43], v[14:15], v[4:5], v[42:43]
	s_waitcnt vmcnt(12)
	v_mov_b32_e32 v48, v174
	v_mov_b32_e32 v49, v175
	v_mov_b32_e32 v50, v176
	v_mov_b32_e32 v51, v177
	v_pk_fma_f32 v[48:49], v[10:11], v[6:7], v[48:49]
	v_pk_fma_f32 v[44:45], v[16:17], v[2:3], v[44:45]
	v_pk_fma_f32 v[50:51], v[12:13], v[8:9], v[50:51]
	v_cvt_pk_bf16_f32 v2, v42, v43
	v_cvt_pk_bf16_f32 v3, v44, v45
	v_cvt_pk_bf16_f32 v4, v48, v49
	v_cvt_pk_bf16_f32 v5, v50, v51
	global_store_dwordx4 v[64:65], v[2:5], off offset:1024
	s_nop 0
	s_waitcnt vmcnt(13)
	v_mov_b32_e32 v2, v178
	v_mov_b32_e32 v3, v179
	v_mov_b32_e32 v4, v180
	v_mov_b32_e32 v5, v181
	v_pk_add_f32 v[2:3], v[2:3], 1.0 op_sel_hi:[1,0]
	s_waitcnt vmcnt(13)
	v_mov_b32_e32 v6, v182
	v_mov_b32_e32 v7, v183
	v_mov_b32_e32 v8, v184
	v_mov_b32_e32 v9, v185
	v_pk_add_f32 v[6:7], v[6:7], 1.0 op_sel_hi:[1,0]
	v_pk_add_f32 v[4:5], v[4:5], 1.0 op_sel_hi:[1,0]
	v_pk_add_f32 v[8:9], v[8:9], 1.0 op_sel_hi:[1,0]
	s_waitcnt vmcnt(13)
	v_mov_b32_e32 v10, v186
	v_mov_b32_e32 v11, v187
	v_mov_b32_e32 v12, v188
	v_mov_b32_e32 v13, v189
	v_pk_fma_f32 v[2:3], v[2:3], v[42:43], v[10:11]
	s_waitcnt vmcnt(13)
	v_mov_b32_e32 v14, v190
	v_mov_b32_e32 v15, v191
	v_mov_b32_e32 v16, v192
	v_mov_b32_e32 v17, v193
	v_pk_fma_f32 v[6:7], v[6:7], v[48:49], v[14:15]
	v_pk_fma_f32 v[4:5], v[4:5], v[44:45], v[12:13]
	v_pk_fma_f32 v[8:9], v[8:9], v[50:51], v[16:17]
	v_cvt_pk_bf16_f32 v2, v2, v3
	v_cvt_pk_bf16_f32 v3, v4, v5
	v_cvt_pk_bf16_f32 v4, v6, v7
	v_cvt_pk_bf16_f32 v5, v8, v9
	global_store_dwordx4 v[38:39], v[2:5], off offset:1024
	s_andn2_b64 exec, exec, s[4:5]
	s_cbranch_execnz .LBB0_1364
